# branch-GEMM phase: odd workgroups start 9 us late instead of 6 us
# speedup vs baseline: 1.0035x; 1.0019x over previous
.LBB0_779:
	s_cmp_le_i32 s76, s18
	s_cselect_b64 s[0:1], -1, 0
	s_and_b64 s[2:3], s[0:1], s[4:5]
	v_readlane_b32 s0, v236, 1
	s_mul_i32 s0, s0, 7
	s_add_i32 s29, s0, 6
	s_cmp_lt_i32 s29, s77
	s_cselect_b64 s[0:1], -1, 0
	s_andn2_b64 vcc, exec, s[2:3]
	s_cbranch_vccnz .LBB0_920
	v_readlane_b32 s98, v237, 48
	s_and_b32 s98, s98, 1
	s_cmp_eq_u32 s98, 0
	s_cbranch_scc1 .Lstg_skipp
	s_memrealtime s[98:99]
	s_waitcnt lgkmcnt(0)
	s_add_u32 s100, s98, 0x384
